# P1 epilogue bpermute lane-index hoist + attention row-max: max over S_A first with short nop, max3-only tree, 3-op cross-half exchange
# speedup vs baseline: 1.0104x; 1.0069x over previous
.LBB0_501:
	v_and_b32_e32 v254, 64, v195
	v_xor_b32_e32 v255, 16, v195
	v_add_u32_e32 v254, 64, v254
	v_cmp_lt_i32_e32 vcc, v255, v254
	s_nop 1
	v_cndmask_b32_e32 v255, v195, v255, vcc
	v_lshlrev_b32_e32 v252, 2, v255
	v_xor_b32_e32 v255, 32, v195
	v_cmp_lt_i32_e32 vcc, v255, v254
	s_nop 1
	v_cndmask_b32_e32 v255, v195, v255, vcc
	v_lshlrev_b32_e32 v253, 2, v255
	s_lshl_b32 s76, s10, 8
	s_add_i32 s76, s76, s97
	v_or_b32_e32 v184, s76, v149
	v_ashrrev_i32_e32 v185, 31, v184
	v_lshl_add_u64 v[0:1], v[184:185], 2, s[26:27]
	global_load_dword v150, v[0:1], off
	global_load_dword v241, v[0:1], off offset:64
	global_load_dword v242, v[0:1], off offset:128
	global_load_dword v243, v[0:1], off offset:192
	global_load_dword v244, v[0:1], off offset:512
	global_load_dword v245, v[0:1], off offset:576
	global_load_dword v246, v[0:1], off offset:640
	global_load_dword v247, v[0:1], off offset:704
	s_xor_b64 s[12:13], s[12:13], -1
	s_xor_b64 s[72:73], s[70:71], -1
	v_lshl_add_u64 v[178:179], s[14:15], 0, v[152:153]
	s_mov_b64 s[10:11], -1
	s_and_b64 vcc, exec, s[12:13]
	s_cbranch_vccz .LBB0_510
	s_and_b64 vcc, exec, s[72:73]
	s_cbranch_vccz .LBB0_507
	s_and_saveexec_b64 s[10:11], s[6:7]
	s_cbranch_execz .LBB0_506
	s_waitcnt vmcnt(0)
	v_mul_f32_e32 v0, v16, v150
	v_mul_f32_e32 v0, 0xbfb8aa3b, v0
	v_mul_f32_e32 v1, v17, v150
	v_exp_f32_e32 v0, v0
	v_mul_f32_e32 v1, 0xbfb8aa3b, v1
	v_exp_f32_e32 v1, v1
	v_mul_f32_e32 v3, v19, v150
	v_add_f32_e32 v0, 1.0, v0
	v_rcp_f32_e32 v2, v0
	v_add_f32_e32 v0, 1.0, v1
	v_mul_f32_e32 v1, v18, v150
	v_mul_f32_e32 v1, 0xbfb8aa3b, v1
	v_exp_f32_e32 v1, v1
	v_mul_f32_e32 v3, 0xbfb8aa3b, v3
	v_exp_f32_e32 v5, v3
	v_rcp_f32_e32 v3, v0
	v_add_f32_e32 v0, 1.0, v1
	v_mul_f32_e32 v1, v20, v150
	v_rcp_f32_e32 v4, v0
	v_add_f32_e32 v0, 1.0, v5
	v_mul_f32_e32 v1, 0xbfb8aa3b, v1
	v_mul_f32_e32 v5, v21, v150
	v_exp_f32_e32 v1, v1
	v_mul_f32_e32 v5, 0xbfb8aa3b, v5
	v_exp_f32_e32 v7, v5
	v_rcp_f32_e32 v5, v0
	v_add_f32_e32 v0, 1.0, v1
	v_mul_f32_e32 v1, v22, v150
	v_rcp_f32_e32 v6, v0
	v_add_f32_e32 v0, 1.0, v7
	v_mul_f32_e32 v1, 0xbfb8aa3b, v1
	v_mul_f32_e32 v7, v23, v150
	v_exp_f32_e32 v1, v1
	v_mul_f32_e32 v7, 0xbfb8aa3b, v7
	v_exp_f32_e32 v9, v7
	v_rcp_f32_e32 v7, v0
	v_add_f32_e32 v0, 1.0, v1
	v_rcp_f32_e32 v8, v0
	v_add_f32_e32 v0, 1.0, v9
	v_rcp_f32_e32 v9, v0
	v_lshlrev_b64 v[0:1], 7, v[184:185]
	v_lshl_add_u64 v[0:1], v[154:155], 0, v[0:1]
	global_store_dwordx4 v[0:1], v[2:5], off
	global_store_dwordx4 v[0:1], v[6:9], off offset:16
	s_and_b64 exec, exec, s[8:9]
	s_cbranch_execz .LBB0_506
	v_mul_f32_e32 v2, v24, v150
	v_mul_f32_e32 v3, v25, v150
	v_mul_f32_e32 v4, v26, v150
	v_mul_f32_e32 v5, v27, v150
	v_mul_f32_e32 v2, 0xbfb8aa3b, v2
	v_mul_f32_e32 v3, 0xbfb8aa3b, v3
	v_mul_f32_e32 v4, 0xbfb8aa3b, v4
	v_mul_f32_e32 v5, 0xbfb8aa3b, v5
	v_mul_f32_e32 v6, v28, v150
	v_mul_f32_e32 v7, v29, v150
	v_mul_f32_e32 v8, v30, v150
	v_mul_f32_e32 v9, v31, v150
	v_exp_f32_e32 v2, v2
	v_exp_f32_e32 v3, v3
	v_exp_f32_e32 v4, v4
	v_exp_f32_e32 v5, v5
	v_mul_f32_e32 v6, 0xbfb8aa3b, v6
	v_mul_f32_e32 v7, 0xbfb8aa3b, v7
	v_mul_f32_e32 v8, 0xbfb8aa3b, v8
	v_mul_f32_e32 v9, 0xbfb8aa3b, v9
	v_exp_f32_e32 v6, v6
	v_exp_f32_e32 v7, v7
	v_exp_f32_e32 v8, v8
	v_exp_f32_e32 v9, v9
	v_add_f32_e32 v2, 1.0, v2
	v_add_f32_e32 v3, 1.0, v3
	v_add_f32_e32 v4, 1.0, v4
	v_add_f32_e32 v5, 1.0, v5
	v_rcp_f32_e32 v2, v2
	v_rcp_f32_e32 v3, v3
	v_rcp_f32_e32 v4, v4
	v_rcp_f32_e32 v5, v5
	v_add_f32_e32 v6, 1.0, v6
	v_add_f32_e32 v7, 1.0, v7
	v_add_f32_e32 v8, 1.0, v8
	v_add_f32_e32 v9, 1.0, v9
	v_rcp_f32_e32 v6, v6
	v_rcp_f32_e32 v7, v7
	v_rcp_f32_e32 v8, v8
	v_rcp_f32_e32 v9, v9
	global_store_dwordx4 v[0:1], v[2:5], off offset:32
	global_store_dwordx4 v[0:1], v[6:9], off offset:48

.LBB0_510:
	s_and_b64 s[70:71], s[8:9], s[4:5]
	s_ashr_i32 s4, s76, 11
	s_mul_i32 s4, s65, s4
	s_add_i32 s4, s4, s63
	s_ashr_i32 s5, s4, 31
	v_lshl_add_u64 v[180:181], v[178:179], 0, v[152:153]
	s_lshl_b64 s[4:5], s[4:5], 18
	v_cndmask_b32_e64 v0, 0, 1, s[74:75]
	v_lshl_add_u64 v[182:183], v[180:181], 0, s[4:5]
	s_andn2_b64 vcc, exec, s[10:11]
	v_cmp_ne_u32_e64 s[10:11], 1, v0
	s_cbranch_vccnz .LBB0_517
	s_and_b64 vcc, exec, s[10:11]
	s_cbranch_vccnz .LBB0_632
	v_mul_f32_e32 v4, v17, v17
	v_fmac_f32_e32 v4, v16, v16
	v_fmac_f32_e32 v4, v18, v18
	v_fmac_f32_e32 v4, v19, v19
	v_fmac_f32_e32 v4, v20, v20
	v_fmac_f32_e32 v4, v21, v21
	v_fmac_f32_e32 v4, v22, v22
	v_fmac_f32_e32 v4, v23, v23
	v_pk_mul_f32 v[2:3], v[24:25], v[24:25]
	v_pk_mul_f32 v[0:1], v[26:27], v[26:27]
	v_add_f32_e32 v2, v2, v4
	v_add_f32_e32 v2, v3, v2
	v_add_f32_e32 v0, v0, v2
	v_add_f32_e32 v4, v1, v0
	v_pk_mul_f32 v[2:3], v[28:29], v[28:29]
	v_pk_mul_f32 v[0:1], v[30:31], v[30:31]
	v_add_f32_e32 v2, v2, v4
	v_add_f32_e32 v2, v3, v2
	v_add_f32_e32 v0, v0, v2
	v_add_f32_e32 v0, v1, v0
	ds_bpermute_b32 v1, v252, v0
	s_waitcnt lgkmcnt(0)
	v_add_f32_e32 v0, v0, v1
	ds_bpermute_b32 v1, v253, v0
	s_waitcnt lgkmcnt(0)
	v_add_f32_e32 v0, v0, v1
	s_waitcnt vmcnt(0)
	v_mul_f32_e32 v1, v150, v150
	v_mul_f32_e32 v0, v1, v0
	v_fmamk_f32 v0, v0, 0x3c800000, v194
	v_mul_f32_e32 v1, 0x4b800000, v0
	v_cmp_gt_f32_e32 vcc, s42, v0
	s_nop 1
	v_cndmask_b32_e32 v0, v0, v1, vcc
	v_rsq_f32_e32 v0, v0
	s_nop 0
	v_mul_f32_e32 v1, 0x45800000, v0
	v_cndmask_b32_e32 v0, v0, v1, vcc
	v_mul_f32_e32 v0, v150, v0
	v_pk_mul_f32 v[186:187], v[16:17], v[0:1] op_sel_hi:[1,0]
	v_pk_mul_f32 v[2:3], v[18:19], v[0:1] op_sel_hi:[1,0]
	v_pk_mul_f32 v[4:5], v[20:21], v[0:1] op_sel_hi:[1,0]
	v_pk_mul_f32 v[6:7], v[22:23], v[0:1] op_sel_hi:[1,0]
	v_pk_mul_f32 v[8:9], v[24:25], v[0:1] op_sel_hi:[1,0]
	v_pk_mul_f32 v[10:11], v[26:27], v[0:1] op_sel_hi:[1,0]
	v_pk_mul_f32 v[12:13], v[28:29], v[0:1] op_sel_hi:[1,0]
	v_pk_mul_f32 v[0:1], v[30:31], v[0:1] op_sel_hi:[1,0]
	v_pk_mul_f32 v[12:13], v[174:175], v[12:13]
	v_pk_mul_f32 v[14:15], v[176:177], v[0:1]
	v_pk_mul_f32 v[10:11], v[172:173], v[10:11]
	v_pk_mul_f32 v[8:9], v[170:171], v[8:9]
	v_pk_mul_f32 v[6:7], v[168:169], v[6:7]
	v_pk_mul_f32 v[4:5], v[166:167], v[4:5]
	v_pk_mul_f32 v[2:3], v[164:165], v[2:3]
	v_pk_mul_f32 v[0:1], v[162:163], v[186:187]
	s_cbranch_execnz .LBB0_514

.LBB0_526:
	s_andn2_b64 vcc, exec, s[4:5]
	s_cbranch_vccnz .LBB0_533
	s_and_b64 vcc, exec, s[10:11]
	s_cbranch_vccnz .LBB0_633
	v_mul_f32_e32 v4, v129, v129
	v_fmac_f32_e32 v4, v128, v128
	v_fmac_f32_e32 v4, v130, v130
	v_fmac_f32_e32 v4, v131, v131
	v_fmac_f32_e32 v4, v132, v132
	v_fmac_f32_e32 v4, v133, v133
	v_fmac_f32_e32 v4, v134, v134
	v_fmac_f32_e32 v4, v135, v135
	v_pk_mul_f32 v[2:3], v[136:137], v[136:137]
	v_pk_mul_f32 v[0:1], v[138:139], v[138:139]
	v_add_f32_e32 v2, v2, v4
	v_add_f32_e32 v2, v3, v2
	v_add_f32_e32 v0, v0, v2
	v_add_f32_e32 v4, v1, v0
	v_pk_mul_f32 v[2:3], v[140:141], v[140:141]
	v_pk_mul_f32 v[0:1], v[142:143], v[142:143]
	v_add_f32_e32 v2, v2, v4
	v_add_f32_e32 v2, v3, v2
	v_add_f32_e32 v0, v0, v2
	v_add_f32_e32 v0, v1, v0
	ds_bpermute_b32 v1, v252, v0
	s_waitcnt lgkmcnt(0)
	v_add_f32_e32 v0, v0, v1
	ds_bpermute_b32 v1, v253, v0
	s_waitcnt lgkmcnt(0)
	v_add_f32_e32 v0, v0, v1
	v_mul_f32_e32 v1, v16, v16
	v_mul_f32_e32 v0, v1, v0
	v_fmamk_f32 v0, v0, 0x3c800000, v194
	v_mul_f32_e32 v1, 0x4b800000, v0
	v_cmp_gt_f32_e32 vcc, s42, v0
	s_nop 1
	v_cndmask_b32_e32 v0, v0, v1, vcc
	v_rsq_f32_e32 v0, v0
	s_nop 0
	v_mul_f32_e32 v1, 0x45800000, v0
	v_cndmask_b32_e32 v0, v0, v1, vcc
	v_mul_f32_e32 v0, v16, v0
	v_pk_mul_f32 v[18:19], v[128:129], v[0:1] op_sel_hi:[1,0]
	v_pk_mul_f32 v[2:3], v[130:131], v[0:1] op_sel_hi:[1,0]
	v_pk_mul_f32 v[4:5], v[132:133], v[0:1] op_sel_hi:[1,0]
	v_pk_mul_f32 v[6:7], v[134:135], v[0:1] op_sel_hi:[1,0]
	v_pk_mul_f32 v[8:9], v[136:137], v[0:1] op_sel_hi:[1,0]
	v_pk_mul_f32 v[10:11], v[138:139], v[0:1] op_sel_hi:[1,0]
	v_pk_mul_f32 v[12:13], v[140:141], v[0:1] op_sel_hi:[1,0]
	v_pk_mul_f32 v[0:1], v[142:143], v[0:1] op_sel_hi:[1,0]
	v_pk_mul_f32 v[12:13], v[174:175], v[12:13]
	v_pk_mul_f32 v[14:15], v[176:177], v[0:1]
	v_pk_mul_f32 v[10:11], v[172:173], v[10:11]
	v_pk_mul_f32 v[8:9], v[170:171], v[8:9]
	v_pk_mul_f32 v[6:7], v[168:169], v[6:7]
	v_pk_mul_f32 v[4:5], v[166:167], v[4:5]
	v_pk_mul_f32 v[2:3], v[164:165], v[2:3]
	v_pk_mul_f32 v[0:1], v[162:163], v[18:19]
	s_cbranch_execnz .LBB0_530

.LBB0_542:
	s_andn2_b64 vcc, exec, s[4:5]
	s_cbranch_vccnz .LBB0_549
	s_and_b64 vcc, exec, s[10:11]
	s_cbranch_vccnz .LBB0_634
	v_mul_f32_e32 v4, v113, v113
	v_fmac_f32_e32 v4, v112, v112
	v_fmac_f32_e32 v4, v114, v114
	v_fmac_f32_e32 v4, v115, v115
	v_fmac_f32_e32 v4, v116, v116
	v_fmac_f32_e32 v4, v117, v117
	v_fmac_f32_e32 v4, v118, v118
	v_fmac_f32_e32 v4, v119, v119
	v_pk_mul_f32 v[2:3], v[120:121], v[120:121]
	v_pk_mul_f32 v[0:1], v[122:123], v[122:123]
	v_add_f32_e32 v2, v2, v4
	v_add_f32_e32 v2, v3, v2
	v_add_f32_e32 v0, v0, v2
	v_add_f32_e32 v4, v1, v0
	v_pk_mul_f32 v[2:3], v[124:125], v[124:125]
	v_pk_mul_f32 v[0:1], v[126:127], v[126:127]
	v_add_f32_e32 v2, v2, v4
	v_add_f32_e32 v2, v3, v2
	v_add_f32_e32 v0, v0, v2
	v_add_f32_e32 v0, v1, v0
	ds_bpermute_b32 v1, v252, v0
	s_waitcnt lgkmcnt(0)
	v_add_f32_e32 v0, v0, v1
	ds_bpermute_b32 v1, v253, v0
	s_waitcnt lgkmcnt(0)
	v_add_f32_e32 v0, v0, v1
	v_mul_f32_e32 v1, v16, v16
	v_mul_f32_e32 v0, v1, v0
	v_fmamk_f32 v0, v0, 0x3c800000, v194
	v_mul_f32_e32 v1, 0x4b800000, v0
	v_cmp_gt_f32_e32 vcc, s42, v0
	s_nop 1
	v_cndmask_b32_e32 v0, v0, v1, vcc
	v_rsq_f32_e32 v0, v0
	s_nop 0
	v_mul_f32_e32 v1, 0x45800000, v0
	v_cndmask_b32_e32 v0, v0, v1, vcc
	v_mul_f32_e32 v0, v16, v0
	v_pk_mul_f32 v[18:19], v[112:113], v[0:1] op_sel_hi:[1,0]
	v_pk_mul_f32 v[2:3], v[114:115], v[0:1] op_sel_hi:[1,0]
	v_pk_mul_f32 v[4:5], v[116:117], v[0:1] op_sel_hi:[1,0]
	v_pk_mul_f32 v[6:7], v[118:119], v[0:1] op_sel_hi:[1,0]
	v_pk_mul_f32 v[8:9], v[120:121], v[0:1] op_sel_hi:[1,0]
	v_pk_mul_f32 v[10:11], v[122:123], v[0:1] op_sel_hi:[1,0]
	v_pk_mul_f32 v[12:13], v[124:125], v[0:1] op_sel_hi:[1,0]
	v_pk_mul_f32 v[0:1], v[126:127], v[0:1] op_sel_hi:[1,0]
	v_pk_mul_f32 v[12:13], v[174:175], v[12:13]
	v_pk_mul_f32 v[14:15], v[176:177], v[0:1]
	v_pk_mul_f32 v[10:11], v[172:173], v[10:11]
	v_pk_mul_f32 v[8:9], v[170:171], v[8:9]
	v_pk_mul_f32 v[6:7], v[168:169], v[6:7]
	v_pk_mul_f32 v[4:5], v[166:167], v[4:5]
	v_pk_mul_f32 v[2:3], v[164:165], v[2:3]
	v_pk_mul_f32 v[0:1], v[162:163], v[18:19]
	s_cbranch_execnz .LBB0_546

.LBB0_558:
	s_andn2_b64 vcc, exec, s[4:5]
	s_cbranch_vccnz .LBB0_565
	s_and_b64 vcc, exec, s[10:11]
	s_cbranch_vccnz .LBB0_635
	v_mul_f32_e32 v4, v97, v97
	v_fmac_f32_e32 v4, v96, v96
	v_fmac_f32_e32 v4, v98, v98
	v_fmac_f32_e32 v4, v99, v99
	v_fmac_f32_e32 v4, v100, v100
	v_fmac_f32_e32 v4, v101, v101
	v_fmac_f32_e32 v4, v102, v102
	v_fmac_f32_e32 v4, v103, v103
	v_pk_mul_f32 v[2:3], v[104:105], v[104:105]
	v_pk_mul_f32 v[0:1], v[106:107], v[106:107]
	v_add_f32_e32 v2, v2, v4
	v_add_f32_e32 v2, v3, v2
	v_add_f32_e32 v0, v0, v2
	v_add_f32_e32 v4, v1, v0
	v_pk_mul_f32 v[2:3], v[108:109], v[108:109]
	v_pk_mul_f32 v[0:1], v[110:111], v[110:111]
	v_add_f32_e32 v2, v2, v4
	v_add_f32_e32 v2, v3, v2
	v_add_f32_e32 v0, v0, v2
	v_add_f32_e32 v0, v1, v0
	ds_bpermute_b32 v1, v252, v0
	s_waitcnt lgkmcnt(0)
	v_add_f32_e32 v0, v0, v1
	ds_bpermute_b32 v1, v253, v0
	s_waitcnt lgkmcnt(0)
	v_add_f32_e32 v0, v0, v1
	v_mul_f32_e32 v1, v16, v16
	v_mul_f32_e32 v0, v1, v0
	v_fmamk_f32 v0, v0, 0x3c800000, v194
	v_mul_f32_e32 v1, 0x4b800000, v0
	v_cmp_gt_f32_e32 vcc, s42, v0
	s_nop 1
	v_cndmask_b32_e32 v0, v0, v1, vcc
	v_rsq_f32_e32 v0, v0
	s_nop 0
	v_mul_f32_e32 v1, 0x45800000, v0
	v_cndmask_b32_e32 v0, v0, v1, vcc
	v_mul_f32_e32 v0, v16, v0
	v_pk_mul_f32 v[18:19], v[96:97], v[0:1] op_sel_hi:[1,0]
	v_pk_mul_f32 v[2:3], v[98:99], v[0:1] op_sel_hi:[1,0]
	v_pk_mul_f32 v[4:5], v[100:101], v[0:1] op_sel_hi:[1,0]
	v_pk_mul_f32 v[6:7], v[102:103], v[0:1] op_sel_hi:[1,0]
	v_pk_mul_f32 v[8:9], v[104:105], v[0:1] op_sel_hi:[1,0]
	v_pk_mul_f32 v[10:11], v[106:107], v[0:1] op_sel_hi:[1,0]
	v_pk_mul_f32 v[12:13], v[108:109], v[0:1] op_sel_hi:[1,0]
	v_pk_mul_f32 v[0:1], v[110:111], v[0:1] op_sel_hi:[1,0]
	v_pk_mul_f32 v[12:13], v[174:175], v[12:13]
	v_pk_mul_f32 v[14:15], v[176:177], v[0:1]
	v_pk_mul_f32 v[10:11], v[172:173], v[10:11]
	v_pk_mul_f32 v[8:9], v[170:171], v[8:9]
	v_pk_mul_f32 v[6:7], v[168:169], v[6:7]
	v_pk_mul_f32 v[4:5], v[166:167], v[4:5]
	v_pk_mul_f32 v[2:3], v[164:165], v[2:3]
	v_pk_mul_f32 v[0:1], v[162:163], v[18:19]
	s_cbranch_execnz .LBB0_562

.LBB0_574:
	s_ashr_i32 s72, s76, 11
	s_mul_i32 s65, s65, s72
	s_add_i32 s72, s65, s63
	s_ashr_i32 s73, s72, 31
	s_lshl_b64 s[72:73], s[72:73], 18
	s_andn2_b64 vcc, exec, s[4:5]
	v_lshl_add_u64 v[96:97], v[180:181], 0, s[72:73]
	s_cbranch_vccnz .LBB0_581
	s_and_b64 vcc, exec, s[10:11]
	s_cbranch_vccnz .LBB0_636
	v_mul_f32_e32 v4, v81, v81
	v_fmac_f32_e32 v4, v80, v80
	v_fmac_f32_e32 v4, v82, v82
	v_fmac_f32_e32 v4, v83, v83
	v_fmac_f32_e32 v4, v84, v84
	v_fmac_f32_e32 v4, v85, v85
	v_fmac_f32_e32 v4, v86, v86
	v_fmac_f32_e32 v4, v87, v87
	v_pk_mul_f32 v[2:3], v[88:89], v[88:89]
	v_pk_mul_f32 v[0:1], v[90:91], v[90:91]
	v_add_f32_e32 v2, v2, v4
	v_add_f32_e32 v2, v3, v2
	v_add_f32_e32 v0, v0, v2
	v_add_f32_e32 v4, v1, v0
	v_pk_mul_f32 v[2:3], v[92:93], v[92:93]
	v_pk_mul_f32 v[0:1], v[94:95], v[94:95]
	v_add_f32_e32 v2, v2, v4
	v_add_f32_e32 v2, v3, v2
	v_add_f32_e32 v0, v0, v2
	v_add_f32_e32 v0, v1, v0
	ds_bpermute_b32 v1, v252, v0
	s_waitcnt lgkmcnt(0)
	v_add_f32_e32 v0, v0, v1
	ds_bpermute_b32 v1, v253, v0
	s_waitcnt lgkmcnt(0)
	v_add_f32_e32 v0, v0, v1
	v_mul_f32_e32 v1, v16, v16
	v_mul_f32_e32 v0, v1, v0
	v_fmamk_f32 v0, v0, 0x3c800000, v194
	v_mul_f32_e32 v1, 0x4b800000, v0
	v_cmp_gt_f32_e32 vcc, s42, v0
	s_nop 1
	v_cndmask_b32_e32 v0, v0, v1, vcc
	v_rsq_f32_e32 v0, v0
	s_nop 0
	v_mul_f32_e32 v1, 0x45800000, v0
	v_cndmask_b32_e32 v0, v0, v1, vcc
	v_mul_f32_e32 v0, v16, v0
	v_pk_mul_f32 v[18:19], v[80:81], v[0:1] op_sel_hi:[1,0]
	v_pk_mul_f32 v[2:3], v[82:83], v[0:1] op_sel_hi:[1,0]
	v_pk_mul_f32 v[4:5], v[84:85], v[0:1] op_sel_hi:[1,0]
	v_pk_mul_f32 v[6:7], v[86:87], v[0:1] op_sel_hi:[1,0]
	v_pk_mul_f32 v[8:9], v[88:89], v[0:1] op_sel_hi:[1,0]
	v_pk_mul_f32 v[10:11], v[90:91], v[0:1] op_sel_hi:[1,0]
	v_pk_mul_f32 v[12:13], v[92:93], v[0:1] op_sel_hi:[1,0]
	v_pk_mul_f32 v[0:1], v[94:95], v[0:1] op_sel_hi:[1,0]
	v_pk_mul_f32 v[12:13], v[174:175], v[12:13]
	v_pk_mul_f32 v[14:15], v[176:177], v[0:1]
	v_pk_mul_f32 v[10:11], v[172:173], v[10:11]
	v_pk_mul_f32 v[8:9], v[170:171], v[8:9]
	v_pk_mul_f32 v[6:7], v[168:169], v[6:7]
	v_pk_mul_f32 v[4:5], v[166:167], v[4:5]
	v_pk_mul_f32 v[2:3], v[164:165], v[2:3]
	v_pk_mul_f32 v[0:1], v[162:163], v[18:19]
	s_cbranch_execnz .LBB0_578

.LBB0_590:
	s_andn2_b64 vcc, exec, s[4:5]
	s_cbranch_vccnz .LBB0_597
	s_and_b64 vcc, exec, s[10:11]
	s_cbranch_vccnz .LBB0_637
	v_mul_f32_e32 v4, v65, v65
	v_fmac_f32_e32 v4, v64, v64
	v_fmac_f32_e32 v4, v66, v66
	v_fmac_f32_e32 v4, v67, v67
	v_fmac_f32_e32 v4, v68, v68
	v_fmac_f32_e32 v4, v69, v69
	v_fmac_f32_e32 v4, v70, v70
	v_fmac_f32_e32 v4, v71, v71
	v_pk_mul_f32 v[2:3], v[72:73], v[72:73]
	v_pk_mul_f32 v[0:1], v[74:75], v[74:75]
	v_add_f32_e32 v2, v2, v4
	v_add_f32_e32 v2, v3, v2
	v_add_f32_e32 v0, v0, v2
	v_add_f32_e32 v4, v1, v0
	v_pk_mul_f32 v[2:3], v[76:77], v[76:77]
	v_pk_mul_f32 v[0:1], v[78:79], v[78:79]
	v_add_f32_e32 v2, v2, v4
	v_add_f32_e32 v2, v3, v2
	v_add_f32_e32 v0, v0, v2
	v_add_f32_e32 v0, v1, v0
	ds_bpermute_b32 v1, v252, v0
	s_waitcnt lgkmcnt(0)
	v_add_f32_e32 v0, v0, v1
	ds_bpermute_b32 v1, v253, v0
	s_waitcnt lgkmcnt(0)
	v_add_f32_e32 v0, v0, v1
	v_mul_f32_e32 v1, v16, v16
	v_mul_f32_e32 v0, v1, v0
	v_fmamk_f32 v0, v0, 0x3c800000, v194
	v_mul_f32_e32 v1, 0x4b800000, v0
	v_cmp_gt_f32_e32 vcc, s42, v0
	s_nop 1
	v_cndmask_b32_e32 v0, v0, v1, vcc
	v_rsq_f32_e32 v0, v0
	s_nop 0
	v_mul_f32_e32 v1, 0x45800000, v0
	v_cndmask_b32_e32 v0, v0, v1, vcc
	v_mul_f32_e32 v0, v16, v0
	v_pk_mul_f32 v[18:19], v[64:65], v[0:1] op_sel_hi:[1,0]
	v_pk_mul_f32 v[2:3], v[66:67], v[0:1] op_sel_hi:[1,0]
	v_pk_mul_f32 v[4:5], v[68:69], v[0:1] op_sel_hi:[1,0]
	v_pk_mul_f32 v[6:7], v[70:71], v[0:1] op_sel_hi:[1,0]
	v_pk_mul_f32 v[8:9], v[72:73], v[0:1] op_sel_hi:[1,0]
	v_pk_mul_f32 v[10:11], v[74:75], v[0:1] op_sel_hi:[1,0]
	v_pk_mul_f32 v[12:13], v[76:77], v[0:1] op_sel_hi:[1,0]
	v_pk_mul_f32 v[0:1], v[78:79], v[0:1] op_sel_hi:[1,0]
	v_pk_mul_f32 v[12:13], v[174:175], v[12:13]
	v_pk_mul_f32 v[14:15], v[176:177], v[0:1]
	v_pk_mul_f32 v[10:11], v[172:173], v[10:11]
	v_pk_mul_f32 v[8:9], v[170:171], v[8:9]
	v_pk_mul_f32 v[6:7], v[168:169], v[6:7]
	v_pk_mul_f32 v[4:5], v[166:167], v[4:5]
	v_pk_mul_f32 v[2:3], v[164:165], v[2:3]
	v_pk_mul_f32 v[0:1], v[162:163], v[18:19]
	s_cbranch_execnz .LBB0_594

.LBB0_606:
	s_andn2_b64 vcc, exec, s[4:5]
	s_cbranch_vccnz .LBB0_613
	s_and_b64 vcc, exec, s[10:11]
	s_cbranch_vccnz .LBB0_638
	v_mul_f32_e32 v4, v49, v49
	v_fmac_f32_e32 v4, v48, v48
	v_fmac_f32_e32 v4, v50, v50
	v_fmac_f32_e32 v4, v51, v51
	v_fmac_f32_e32 v4, v52, v52
	v_fmac_f32_e32 v4, v53, v53
	v_fmac_f32_e32 v4, v54, v54
	v_fmac_f32_e32 v4, v55, v55
	v_pk_mul_f32 v[2:3], v[56:57], v[56:57]
	v_pk_mul_f32 v[0:1], v[58:59], v[58:59]
	v_add_f32_e32 v2, v2, v4
	v_add_f32_e32 v2, v3, v2
	v_add_f32_e32 v0, v0, v2
	v_add_f32_e32 v4, v1, v0
	v_pk_mul_f32 v[2:3], v[60:61], v[60:61]
	v_pk_mul_f32 v[0:1], v[62:63], v[62:63]
	v_add_f32_e32 v2, v2, v4
	v_add_f32_e32 v2, v3, v2
	v_add_f32_e32 v0, v0, v2
	v_add_f32_e32 v0, v1, v0
	ds_bpermute_b32 v1, v252, v0
	s_waitcnt lgkmcnt(0)
	v_add_f32_e32 v0, v0, v1
	ds_bpermute_b32 v1, v253, v0
	s_waitcnt lgkmcnt(0)
	v_add_f32_e32 v0, v0, v1
	v_mul_f32_e32 v1, v16, v16
	v_mul_f32_e32 v0, v1, v0
	v_fmamk_f32 v0, v0, 0x3c800000, v194
	v_mul_f32_e32 v1, 0x4b800000, v0
	v_cmp_gt_f32_e32 vcc, s42, v0
	s_nop 1
	v_cndmask_b32_e32 v0, v0, v1, vcc
	v_rsq_f32_e32 v0, v0
	s_nop 0
	v_mul_f32_e32 v1, 0x45800000, v0
	v_cndmask_b32_e32 v0, v0, v1, vcc
	v_mul_f32_e32 v0, v16, v0
	v_pk_mul_f32 v[18:19], v[48:49], v[0:1] op_sel_hi:[1,0]
	v_pk_mul_f32 v[2:3], v[50:51], v[0:1] op_sel_hi:[1,0]
	v_pk_mul_f32 v[4:5], v[52:53], v[0:1] op_sel_hi:[1,0]
	v_pk_mul_f32 v[6:7], v[54:55], v[0:1] op_sel_hi:[1,0]
	v_pk_mul_f32 v[8:9], v[56:57], v[0:1] op_sel_hi:[1,0]
	v_pk_mul_f32 v[10:11], v[58:59], v[0:1] op_sel_hi:[1,0]
	v_pk_mul_f32 v[12:13], v[60:61], v[0:1] op_sel_hi:[1,0]
	v_pk_mul_f32 v[0:1], v[62:63], v[0:1] op_sel_hi:[1,0]
	v_pk_mul_f32 v[12:13], v[174:175], v[12:13]
	v_pk_mul_f32 v[14:15], v[176:177], v[0:1]
	v_pk_mul_f32 v[10:11], v[172:173], v[10:11]
	v_pk_mul_f32 v[8:9], v[170:171], v[8:9]
	v_pk_mul_f32 v[6:7], v[168:169], v[6:7]
	v_pk_mul_f32 v[4:5], v[166:167], v[4:5]
	v_pk_mul_f32 v[2:3], v[164:165], v[2:3]
	v_pk_mul_f32 v[0:1], v[162:163], v[18:19]
	s_cbranch_execnz .LBB0_610

.LBB0_622:
	s_andn2_b64 vcc, exec, s[4:5]
	s_cbranch_vccnz .LBB0_629
	s_and_b64 vcc, exec, s[10:11]
	s_cbranch_vccnz .LBB0_639
	v_mul_f32_e32 v4, v37, v37
	v_fmac_f32_e32 v4, v36, v36
	v_fmac_f32_e32 v4, v38, v38
	v_fmac_f32_e32 v4, v39, v39
	v_fmac_f32_e32 v4, v40, v40
	v_fmac_f32_e32 v4, v41, v41
	v_fmac_f32_e32 v4, v42, v42
	v_fmac_f32_e32 v4, v43, v43
	v_pk_mul_f32 v[2:3], v[44:45], v[44:45]
	v_pk_mul_f32 v[0:1], v[46:47], v[46:47]
	v_add_f32_e32 v2, v2, v4
	v_add_f32_e32 v2, v3, v2
	v_add_f32_e32 v0, v0, v2
	v_add_f32_e32 v4, v1, v0
	v_pk_mul_f32 v[2:3], v[32:33], v[32:33]
	v_pk_mul_f32 v[0:1], v[34:35], v[34:35]
	v_add_f32_e32 v2, v2, v4
	v_add_f32_e32 v2, v3, v2
	v_add_f32_e32 v0, v0, v2
	v_add_f32_e32 v0, v1, v0
	ds_bpermute_b32 v1, v252, v0
	s_waitcnt lgkmcnt(0)
	v_add_f32_e32 v0, v0, v1
	ds_bpermute_b32 v1, v253, v0
	s_waitcnt lgkmcnt(0)
	v_add_f32_e32 v0, v0, v1
	v_mul_f32_e32 v1, v16, v16
	v_mul_f32_e32 v0, v1, v0
	v_fmamk_f32 v0, v0, 0x3c800000, v194
	v_mul_f32_e32 v1, 0x4b800000, v0
	v_cmp_gt_f32_e32 vcc, s42, v0
	s_nop 1
	v_cndmask_b32_e32 v0, v0, v1, vcc
	v_rsq_f32_e32 v0, v0
	s_nop 0
	v_mul_f32_e32 v1, 0x45800000, v0
	v_cndmask_b32_e32 v0, v0, v1, vcc
	v_mul_f32_e32 v0, v16, v0
	v_pk_mul_f32 v[18:19], v[36:37], v[0:1] op_sel_hi:[1,0]
	v_pk_mul_f32 v[2:3], v[38:39], v[0:1] op_sel_hi:[1,0]
	v_pk_mul_f32 v[4:5], v[40:41], v[0:1] op_sel_hi:[1,0]
	v_pk_mul_f32 v[6:7], v[42:43], v[0:1] op_sel_hi:[1,0]
	v_pk_mul_f32 v[8:9], v[44:45], v[0:1] op_sel_hi:[1,0]
	v_pk_mul_f32 v[10:11], v[46:47], v[0:1] op_sel_hi:[1,0]
	v_pk_mul_f32 v[12:13], v[32:33], v[0:1] op_sel_hi:[1,0]
	v_pk_mul_f32 v[0:1], v[34:35], v[0:1] op_sel_hi:[1,0]
	v_pk_mul_f32 v[12:13], v[174:175], v[12:13]
	v_pk_mul_f32 v[14:15], v[176:177], v[0:1]
	v_pk_mul_f32 v[10:11], v[172:173], v[10:11]
	v_pk_mul_f32 v[8:9], v[170:171], v[8:9]
	v_pk_mul_f32 v[6:7], v[168:169], v[6:7]
	v_pk_mul_f32 v[4:5], v[166:167], v[4:5]
	v_pk_mul_f32 v[2:3], v[164:165], v[2:3]
	v_pk_mul_f32 v[0:1], v[162:163], v[18:19]
	s_cbranch_execnz .LBB0_626

.LBB0_918:
	s_nop 4
	v_max3_f32 v213, v64, v65, v66
	v_max3_f32 v214, v67, v68, v69
	v_max3_f32 v213, v213, v70, v71
	v_max3_f32 v214, v214, v72, v73
	v_max3_f32 v213, v213, v74, v75
	v_max3_f32 v214, v214, v76, v77
	v_max3_f32 v213, v213, v78, v79
	v_max3_f32 v214, v214, v48, v49
	v_max3_f32 v213, v213, v50, v51
	v_max3_f32 v214, v214, v52, v53
	v_max3_f32 v213, v213, v54, v55
	v_max3_f32 v214, v214, v56, v57
	v_max3_f32 v213, v213, v58, v59
	v_max3_f32 v214, v214, v60, v61
	v_max3_f32 v213, v213, v62, v63
	v_max_f32_e32 v213, v213, v214
	v_mov_b32_e32 v214, v213
	s_nop 1
	v_permlane32_swap_b32_e32 v214, v213
	v_max_f32_e32 v213, v213, v214
	v_cmp_lt_f32_e32 vcc, s92, v213
	s_cbranch_vccz .LBB0_920
	v_max_f32_e32 v32, v213, v213
	v_max_f32_e32 v34, 0, v32
	v_exp_f32_e64 v36, -v34
	v_add_f32_e32 v148, v148, v34
	v_xor_b32_e32 v32, 0x80000000, v148
	v_pk_add_f32 v[64:65], v[64:65], v[34:35] op_sel_hi:[1,0] neg_lo:[0,1] neg_hi:[0,1]
	v_mul_f32_e32 v147, v147, v36
	v_pk_add_f32 v[48:49], v[48:49], v[34:35] op_sel_hi:[1,0] neg_lo:[0,1] neg_hi:[0,1]
	v_pk_add_f32 v[66:67], v[66:67], v[34:35] op_sel_hi:[1,0] neg_lo:[0,1] neg_hi:[0,1]
	v_pk_add_f32 v[50:51], v[50:51], v[34:35] op_sel_hi:[1,0] neg_lo:[0,1] neg_hi:[0,1]
	v_pk_add_f32 v[68:69], v[68:69], v[34:35] op_sel_hi:[1,0] neg_lo:[0,1] neg_hi:[0,1]
	v_pk_add_f32 v[52:53], v[52:53], v[34:35] op_sel_hi:[1,0] neg_lo:[0,1] neg_hi:[0,1]
	v_pk_add_f32 v[70:71], v[70:71], v[34:35] op_sel_hi:[1,0] neg_lo:[0,1] neg_hi:[0,1]
	v_pk_add_f32 v[54:55], v[54:55], v[34:35] op_sel_hi:[1,0] neg_lo:[0,1] neg_hi:[0,1]
	v_pk_add_f32 v[72:73], v[72:73], v[34:35] op_sel_hi:[1,0] neg_lo:[0,1] neg_hi:[0,1]
	v_pk_add_f32 v[56:57], v[56:57], v[34:35] op_sel_hi:[1,0] neg_lo:[0,1] neg_hi:[0,1]
	v_pk_add_f32 v[74:75], v[74:75], v[34:35] op_sel_hi:[1,0] neg_lo:[0,1] neg_hi:[0,1]
	v_pk_add_f32 v[58:59], v[58:59], v[34:35] op_sel_hi:[1,0] neg_lo:[0,1] neg_hi:[0,1]
	v_pk_add_f32 v[76:77], v[76:77], v[34:35] op_sel_hi:[1,0] neg_lo:[0,1] neg_hi:[0,1]
	v_pk_add_f32 v[60:61], v[60:61], v[34:35] op_sel_hi:[1,0] neg_lo:[0,1] neg_hi:[0,1]
	v_pk_add_f32 v[78:79], v[78:79], v[34:35] op_sel_hi:[1,0] neg_lo:[0,1] neg_hi:[0,1]
	v_pk_add_f32 v[62:63], v[62:63], v[34:35] op_sel_hi:[1,0] neg_lo:[0,1] neg_hi:[0,1]
	v_pk_mul_f32 v[14:15], v[14:15], v[36:37] op_sel_hi:[1,0]
	v_pk_mul_f32 v[12:13], v[12:13], v[36:37] op_sel_hi:[1,0]
	v_pk_mul_f32 v[10:11], v[10:11], v[36:37] op_sel_hi:[1,0]
	v_pk_mul_f32 v[8:9], v[8:9], v[36:37] op_sel_hi:[1,0]
	v_pk_mul_f32 v[6:7], v[6:7], v[36:37] op_sel_hi:[1,0]
	v_pk_mul_f32 v[4:5], v[4:5], v[36:37] op_sel_hi:[1,0]
	v_pk_mul_f32 v[2:3], v[2:3], v[36:37] op_sel_hi:[1,0]
	v_pk_mul_f32 v[0:1], v[0:1], v[36:37] op_sel_hi:[1,0]
	v_pk_mul_f32 v[30:31], v[30:31], v[36:37] op_sel_hi:[1,0]
	v_pk_mul_f32 v[28:29], v[28:29], v[36:37] op_sel_hi:[1,0]
	v_pk_mul_f32 v[26:27], v[26:27], v[36:37] op_sel_hi:[1,0]
	v_pk_mul_f32 v[24:25], v[24:25], v[36:37] op_sel_hi:[1,0]
	v_pk_mul_f32 v[22:23], v[22:23], v[36:37] op_sel_hi:[1,0]
	v_pk_mul_f32 v[20:21], v[20:21], v[36:37] op_sel_hi:[1,0]
	v_pk_mul_f32 v[18:19], v[18:19], v[36:37] op_sel_hi:[1,0]
	v_pk_mul_f32 v[16:17], v[16:17], v[36:37] op_sel_hi:[1,0]
	v_mov_b32_e32 v33, v32
	v_mov_b32_e32 v34, v32
	v_mov_b32_e32 v35, v32
	v_mov_b32_e32 v36, v32
	v_mov_b32_e32 v37, v32
	v_mov_b32_e32 v38, v32
	v_mov_b32_e32 v39, v32
	v_mov_b32_e32 v40, v32
	v_mov_b32_e32 v41, v32
	v_mov_b32_e32 v42, v32
	v_mov_b32_e32 v43, v32
	v_mov_b32_e32 v44, v32
	v_mov_b32_e32 v45, v32
	v_mov_b32_e32 v46, v32
	v_mov_b32_e32 v47, v32

.LBB0_933:
	s_nop 4
	v_max3_f32 v149, v64, v65, v66
	v_max3_f32 v212, v67, v68, v69
	v_max3_f32 v149, v149, v70, v71
	v_max3_f32 v212, v212, v72, v73
	v_max3_f32 v149, v149, v74, v75
	v_max3_f32 v212, v212, v76, v77
	v_max3_f32 v149, v149, v78, v79
	v_max3_f32 v212, v212, v48, v49
	v_max3_f32 v149, v149, v50, v51
	v_max3_f32 v212, v212, v52, v53
	v_max3_f32 v149, v149, v54, v55
	v_max3_f32 v212, v212, v56, v57
	v_max3_f32 v149, v149, v58, v59
	v_max3_f32 v212, v212, v60, v61
	v_max3_f32 v149, v149, v62, v63
	v_max_f32_e32 v149, v149, v212
	v_mov_b32_e32 v212, v149
	s_nop 1
	v_permlane32_swap_b32_e32 v212, v149
	v_max_f32_e32 v149, v149, v212
	v_cmp_lt_f32_e32 vcc, s92, v149
	s_cbranch_vccz .LBB0_935
	v_max_f32_e32 v32, v149, v149
	v_max_f32_e32 v34, 0, v32
	v_exp_f32_e64 v36, -v34
	v_add_f32_e32 v148, v148, v34
	v_xor_b32_e32 v32, 0x80000000, v148
	v_pk_add_f32 v[64:65], v[64:65], v[34:35] op_sel_hi:[1,0] neg_lo:[0,1] neg_hi:[0,1]
	v_mul_f32_e32 v147, v147, v36
	v_pk_add_f32 v[48:49], v[48:49], v[34:35] op_sel_hi:[1,0] neg_lo:[0,1] neg_hi:[0,1]
	v_pk_add_f32 v[66:67], v[66:67], v[34:35] op_sel_hi:[1,0] neg_lo:[0,1] neg_hi:[0,1]
	v_pk_add_f32 v[50:51], v[50:51], v[34:35] op_sel_hi:[1,0] neg_lo:[0,1] neg_hi:[0,1]
	v_pk_add_f32 v[68:69], v[68:69], v[34:35] op_sel_hi:[1,0] neg_lo:[0,1] neg_hi:[0,1]
	v_pk_add_f32 v[52:53], v[52:53], v[34:35] op_sel_hi:[1,0] neg_lo:[0,1] neg_hi:[0,1]
	v_pk_add_f32 v[70:71], v[70:71], v[34:35] op_sel_hi:[1,0] neg_lo:[0,1] neg_hi:[0,1]
	v_pk_add_f32 v[54:55], v[54:55], v[34:35] op_sel_hi:[1,0] neg_lo:[0,1] neg_hi:[0,1]
	v_pk_add_f32 v[72:73], v[72:73], v[34:35] op_sel_hi:[1,0] neg_lo:[0,1] neg_hi:[0,1]
	v_pk_add_f32 v[56:57], v[56:57], v[34:35] op_sel_hi:[1,0] neg_lo:[0,1] neg_hi:[0,1]
	v_pk_add_f32 v[74:75], v[74:75], v[34:35] op_sel_hi:[1,0] neg_lo:[0,1] neg_hi:[0,1]
	v_pk_add_f32 v[58:59], v[58:59], v[34:35] op_sel_hi:[1,0] neg_lo:[0,1] neg_hi:[0,1]
	v_pk_add_f32 v[76:77], v[76:77], v[34:35] op_sel_hi:[1,0] neg_lo:[0,1] neg_hi:[0,1]
	v_pk_add_f32 v[60:61], v[60:61], v[34:35] op_sel_hi:[1,0] neg_lo:[0,1] neg_hi:[0,1]
	v_pk_add_f32 v[78:79], v[78:79], v[34:35] op_sel_hi:[1,0] neg_lo:[0,1] neg_hi:[0,1]
	v_pk_add_f32 v[62:63], v[62:63], v[34:35] op_sel_hi:[1,0] neg_lo:[0,1] neg_hi:[0,1]
	v_pk_mul_f32 v[14:15], v[14:15], v[36:37] op_sel_hi:[1,0]
	v_pk_mul_f32 v[12:13], v[12:13], v[36:37] op_sel_hi:[1,0]
	v_pk_mul_f32 v[10:11], v[10:11], v[36:37] op_sel_hi:[1,0]
	v_pk_mul_f32 v[8:9], v[8:9], v[36:37] op_sel_hi:[1,0]
	v_pk_mul_f32 v[6:7], v[6:7], v[36:37] op_sel_hi:[1,0]
	v_pk_mul_f32 v[4:5], v[4:5], v[36:37] op_sel_hi:[1,0]
	v_pk_mul_f32 v[2:3], v[2:3], v[36:37] op_sel_hi:[1,0]
	v_pk_mul_f32 v[0:1], v[0:1], v[36:37] op_sel_hi:[1,0]
	v_pk_mul_f32 v[30:31], v[30:31], v[36:37] op_sel_hi:[1,0]
	v_pk_mul_f32 v[28:29], v[28:29], v[36:37] op_sel_hi:[1,0]
	v_pk_mul_f32 v[26:27], v[26:27], v[36:37] op_sel_hi:[1,0]
	v_pk_mul_f32 v[24:25], v[24:25], v[36:37] op_sel_hi:[1,0]
	v_pk_mul_f32 v[22:23], v[22:23], v[36:37] op_sel_hi:[1,0]
	v_pk_mul_f32 v[20:21], v[20:21], v[36:37] op_sel_hi:[1,0]
	v_pk_mul_f32 v[18:19], v[18:19], v[36:37] op_sel_hi:[1,0]
	v_pk_mul_f32 v[16:17], v[16:17], v[36:37] op_sel_hi:[1,0]
	v_mov_b32_e32 v33, v32
	v_mov_b32_e32 v34, v32
	v_mov_b32_e32 v35, v32
	v_mov_b32_e32 v36, v32
	v_mov_b32_e32 v37, v32
	v_mov_b32_e32 v38, v32
	v_mov_b32_e32 v39, v32
	v_mov_b32_e32 v40, v32
	v_mov_b32_e32 v41, v32
	v_mov_b32_e32 v42, v32
	v_mov_b32_e32 v43, v32
	v_mov_b32_e32 v44, v32
	v_mov_b32_e32 v45, v32
	v_mov_b32_e32 v46, v32
	v_mov_b32_e32 v47, v32

.LBB0_1020:
	s_nop 4
	v_max3_f32 v216, v64, v65, v66
	v_max3_f32 v217, v67, v68, v69
	v_max3_f32 v216, v216, v70, v71
	v_max3_f32 v217, v217, v72, v73
	v_max3_f32 v216, v216, v74, v75
	v_max3_f32 v217, v217, v76, v77
	v_max3_f32 v216, v216, v78, v79
	v_max3_f32 v217, v217, v48, v49
	v_max3_f32 v216, v216, v50, v51
	v_max3_f32 v217, v217, v52, v53
	v_max3_f32 v216, v216, v54, v55
	v_max3_f32 v217, v217, v56, v57
	v_max3_f32 v216, v216, v58, v59
	v_max3_f32 v217, v217, v60, v61
	v_max3_f32 v216, v216, v62, v63
	v_max_f32_e32 v216, v216, v217
	v_mov_b32_e32 v217, v216
	s_nop 1
	v_permlane32_swap_b32_e32 v217, v216
	v_max_f32_e32 v216, v216, v217
	v_cmp_lt_f32_e32 vcc, s92, v216
	s_cbranch_vccz .LBB0_1022
	v_max_f32_e32 v32, v216, v216
	v_max_f32_e32 v34, 0, v32
	v_exp_f32_e64 v36, -v34
	v_add_f32_e32 v215, v215, v34
	v_xor_b32_e32 v32, 0x80000000, v215
	v_pk_add_f32 v[64:65], v[64:65], v[34:35] op_sel_hi:[1,0] neg_lo:[0,1] neg_hi:[0,1]
	v_mul_f32_e32 v214, v214, v36
	v_pk_add_f32 v[48:49], v[48:49], v[34:35] op_sel_hi:[1,0] neg_lo:[0,1] neg_hi:[0,1]
	v_pk_add_f32 v[66:67], v[66:67], v[34:35] op_sel_hi:[1,0] neg_lo:[0,1] neg_hi:[0,1]
	v_pk_add_f32 v[50:51], v[50:51], v[34:35] op_sel_hi:[1,0] neg_lo:[0,1] neg_hi:[0,1]
	v_pk_add_f32 v[68:69], v[68:69], v[34:35] op_sel_hi:[1,0] neg_lo:[0,1] neg_hi:[0,1]
	v_pk_add_f32 v[52:53], v[52:53], v[34:35] op_sel_hi:[1,0] neg_lo:[0,1] neg_hi:[0,1]
	v_pk_add_f32 v[70:71], v[70:71], v[34:35] op_sel_hi:[1,0] neg_lo:[0,1] neg_hi:[0,1]
	v_pk_add_f32 v[54:55], v[54:55], v[34:35] op_sel_hi:[1,0] neg_lo:[0,1] neg_hi:[0,1]
	v_pk_add_f32 v[72:73], v[72:73], v[34:35] op_sel_hi:[1,0] neg_lo:[0,1] neg_hi:[0,1]
	v_pk_add_f32 v[56:57], v[56:57], v[34:35] op_sel_hi:[1,0] neg_lo:[0,1] neg_hi:[0,1]
	v_pk_add_f32 v[74:75], v[74:75], v[34:35] op_sel_hi:[1,0] neg_lo:[0,1] neg_hi:[0,1]
	v_pk_add_f32 v[58:59], v[58:59], v[34:35] op_sel_hi:[1,0] neg_lo:[0,1] neg_hi:[0,1]
	v_pk_add_f32 v[76:77], v[76:77], v[34:35] op_sel_hi:[1,0] neg_lo:[0,1] neg_hi:[0,1]
	v_pk_add_f32 v[60:61], v[60:61], v[34:35] op_sel_hi:[1,0] neg_lo:[0,1] neg_hi:[0,1]
	v_pk_add_f32 v[78:79], v[78:79], v[34:35] op_sel_hi:[1,0] neg_lo:[0,1] neg_hi:[0,1]
	v_pk_add_f32 v[62:63], v[62:63], v[34:35] op_sel_hi:[1,0] neg_lo:[0,1] neg_hi:[0,1]
	v_pk_mul_f32 v[30:31], v[30:31], v[36:37] op_sel_hi:[1,0]
	v_pk_mul_f32 v[28:29], v[28:29], v[36:37] op_sel_hi:[1,0]
	v_pk_mul_f32 v[26:27], v[26:27], v[36:37] op_sel_hi:[1,0]
	v_pk_mul_f32 v[24:25], v[24:25], v[36:37] op_sel_hi:[1,0]
	v_pk_mul_f32 v[22:23], v[22:23], v[36:37] op_sel_hi:[1,0]
	v_pk_mul_f32 v[20:21], v[20:21], v[36:37] op_sel_hi:[1,0]
	v_pk_mul_f32 v[18:19], v[18:19], v[36:37] op_sel_hi:[1,0]
	v_pk_mul_f32 v[16:17], v[16:17], v[36:37] op_sel_hi:[1,0]
	v_pk_mul_f32 v[14:15], v[14:15], v[36:37] op_sel_hi:[1,0]
	v_pk_mul_f32 v[12:13], v[12:13], v[36:37] op_sel_hi:[1,0]
	v_pk_mul_f32 v[10:11], v[10:11], v[36:37] op_sel_hi:[1,0]
	v_pk_mul_f32 v[8:9], v[8:9], v[36:37] op_sel_hi:[1,0]
	v_pk_mul_f32 v[6:7], v[6:7], v[36:37] op_sel_hi:[1,0]
	v_pk_mul_f32 v[4:5], v[4:5], v[36:37] op_sel_hi:[1,0]
	v_pk_mul_f32 v[2:3], v[2:3], v[36:37] op_sel_hi:[1,0]
	v_pk_mul_f32 v[0:1], v[0:1], v[36:37] op_sel_hi:[1,0]
	v_mov_b32_e32 v33, v32
	v_mov_b32_e32 v34, v32
	v_mov_b32_e32 v35, v32
	v_mov_b32_e32 v36, v32
	v_mov_b32_e32 v37, v32
	v_mov_b32_e32 v38, v32
	v_mov_b32_e32 v39, v32
	v_mov_b32_e32 v40, v32
	v_mov_b32_e32 v41, v32
	v_mov_b32_e32 v42, v32
	v_mov_b32_e32 v43, v32
	v_mov_b32_e32 v44, v32
	v_mov_b32_e32 v45, v32
	v_mov_b32_e32 v46, v32
	v_mov_b32_e32 v47, v32

.LBB0_1031:
	s_nop 4
	v_max3_f32 v216, v64, v65, v66
	v_max3_f32 v217, v67, v68, v69
	v_max3_f32 v216, v216, v70, v71
	v_max3_f32 v217, v217, v72, v73
	v_max3_f32 v216, v216, v74, v75
	v_max3_f32 v217, v217, v76, v77
	v_max3_f32 v216, v216, v78, v79
	v_max3_f32 v217, v217, v48, v49
	v_max3_f32 v216, v216, v50, v51
	v_max3_f32 v217, v217, v52, v53
	v_max3_f32 v216, v216, v54, v55
	v_max3_f32 v217, v217, v56, v57
	v_max3_f32 v216, v216, v58, v59
	v_max3_f32 v217, v217, v60, v61
	v_max3_f32 v216, v216, v62, v63
	v_max_f32_e32 v216, v216, v217
	v_mov_b32_e32 v217, v216
	s_nop 1
	v_permlane32_swap_b32_e32 v217, v216
	v_max_f32_e32 v216, v216, v217
	v_cmp_lt_f32_e32 vcc, s92, v216
	s_cbranch_vccz .LBB0_1011
	v_max_f32_e32 v32, v216, v216
	v_max_f32_e32 v34, 0, v32
	v_exp_f32_e64 v36, -v34
	v_add_f32_e32 v215, v215, v34
	v_xor_b32_e32 v32, 0x80000000, v215
	v_pk_add_f32 v[64:65], v[64:65], v[34:35] op_sel_hi:[1,0] neg_lo:[0,1] neg_hi:[0,1]
	v_mul_f32_e32 v214, v214, v36
	v_pk_add_f32 v[48:49], v[48:49], v[34:35] op_sel_hi:[1,0] neg_lo:[0,1] neg_hi:[0,1]
	v_pk_add_f32 v[66:67], v[66:67], v[34:35] op_sel_hi:[1,0] neg_lo:[0,1] neg_hi:[0,1]
	v_pk_add_f32 v[50:51], v[50:51], v[34:35] op_sel_hi:[1,0] neg_lo:[0,1] neg_hi:[0,1]
	v_pk_add_f32 v[68:69], v[68:69], v[34:35] op_sel_hi:[1,0] neg_lo:[0,1] neg_hi:[0,1]
	v_pk_add_f32 v[52:53], v[52:53], v[34:35] op_sel_hi:[1,0] neg_lo:[0,1] neg_hi:[0,1]
	v_pk_add_f32 v[70:71], v[70:71], v[34:35] op_sel_hi:[1,0] neg_lo:[0,1] neg_hi:[0,1]
	v_pk_add_f32 v[54:55], v[54:55], v[34:35] op_sel_hi:[1,0] neg_lo:[0,1] neg_hi:[0,1]
	v_pk_add_f32 v[72:73], v[72:73], v[34:35] op_sel_hi:[1,0] neg_lo:[0,1] neg_hi:[0,1]
	v_pk_add_f32 v[56:57], v[56:57], v[34:35] op_sel_hi:[1,0] neg_lo:[0,1] neg_hi:[0,1]
	v_pk_add_f32 v[74:75], v[74:75], v[34:35] op_sel_hi:[1,0] neg_lo:[0,1] neg_hi:[0,1]
	v_pk_add_f32 v[58:59], v[58:59], v[34:35] op_sel_hi:[1,0] neg_lo:[0,1] neg_hi:[0,1]
	v_pk_add_f32 v[76:77], v[76:77], v[34:35] op_sel_hi:[1,0] neg_lo:[0,1] neg_hi:[0,1]
	v_pk_add_f32 v[60:61], v[60:61], v[34:35] op_sel_hi:[1,0] neg_lo:[0,1] neg_hi:[0,1]
	v_pk_add_f32 v[78:79], v[78:79], v[34:35] op_sel_hi:[1,0] neg_lo:[0,1] neg_hi:[0,1]
	v_pk_add_f32 v[62:63], v[62:63], v[34:35] op_sel_hi:[1,0] neg_lo:[0,1] neg_hi:[0,1]
	v_pk_mul_f32 v[30:31], v[30:31], v[36:37] op_sel_hi:[1,0]
	v_pk_mul_f32 v[28:29], v[28:29], v[36:37] op_sel_hi:[1,0]
	v_pk_mul_f32 v[26:27], v[26:27], v[36:37] op_sel_hi:[1,0]
	v_pk_mul_f32 v[24:25], v[24:25], v[36:37] op_sel_hi:[1,0]
	v_pk_mul_f32 v[22:23], v[22:23], v[36:37] op_sel_hi:[1,0]
	v_pk_mul_f32 v[20:21], v[20:21], v[36:37] op_sel_hi:[1,0]
	v_pk_mul_f32 v[18:19], v[18:19], v[36:37] op_sel_hi:[1,0]
	v_pk_mul_f32 v[16:17], v[16:17], v[36:37] op_sel_hi:[1,0]
	v_pk_mul_f32 v[14:15], v[14:15], v[36:37] op_sel_hi:[1,0]
	v_pk_mul_f32 v[12:13], v[12:13], v[36:37] op_sel_hi:[1,0]
	v_pk_mul_f32 v[10:11], v[10:11], v[36:37] op_sel_hi:[1,0]
	v_pk_mul_f32 v[8:9], v[8:9], v[36:37] op_sel_hi:[1,0]
	v_pk_mul_f32 v[6:7], v[6:7], v[36:37] op_sel_hi:[1,0]
	v_pk_mul_f32 v[4:5], v[4:5], v[36:37] op_sel_hi:[1,0]
	v_pk_mul_f32 v[2:3], v[2:3], v[36:37] op_sel_hi:[1,0]
	v_pk_mul_f32 v[0:1], v[0:1], v[36:37] op_sel_hi:[1,0]
	v_mov_b32_e32 v33, v32
	v_mov_b32_e32 v34, v32
	v_mov_b32_e32 v35, v32
	v_mov_b32_e32 v36, v32
	v_mov_b32_e32 v37, v32
	v_mov_b32_e32 v38, v32
	v_mov_b32_e32 v39, v32
	v_mov_b32_e32 v40, v32
	v_mov_b32_e32 v41, v32
	v_mov_b32_e32 v42, v32
	v_mov_b32_e32 v43, v32
	v_mov_b32_e32 v44, v32
	v_mov_b32_e32 v45, v32
	v_mov_b32_e32 v46, v32
	v_mov_b32_e32 v47, v32
	s_branch .LBB0_1011
